# stagger barrier of trailing half moved to just before its first load segment; xcd barrier after prep
# baseline (speedup 1.0000x reference)
.LBB0_602:
	s_add_u32 s4, s46, 0x80
	s_addc_u32 s5, s47, 0
	s_add_u32 s46, s44, 0x100
	s_addc_u32 s47, s45, 0
	s_mov_b32 s44, 0
	s_andn2_b64 vcc, exec, s[8:9]
	s_cbranch_vccnz .Lnb_603
	s_cmp_eq_u32 s56, 1
	s_cbranch_scc1 .Lnb_603
	s_barrier
.Lnb_603:
	s_add_i32 s76, s44, 2
	s_add_u32 s53, s4, 0x80
	s_addc_u32 s45, s5, 0
	s_add_i32 s54, 0, 0x10000
	s_cmp_eq_u32 s90, s44
	s_cselect_b32 s45, s41, s45
	s_cselect_b32 s44, s40, s53
	v_add_u32_e32 v144, s54, v149
	s_cselect_b32 vcc_hi, s85, s47
	s_cselect_b32 vcc_lo, s84, s46
	s_add_i32 s53, 0, 0x14000
	ds_read_b128 v[140:143], v144
	ds_read_b128 v[152:155], v144 offset:1024
	ds_read_b128 v[156:159], v144 offset:2048
	ds_read_b128 v[166:169], v144 offset:3072
	v_add_u32_e32 v144, s53, v149
	ds_read_b128 v[170:173], v144
	ds_read_b128 v[174:177], v144 offset:1024
	ds_read_b128 v[178:181], v144 offset:2048
	ds_read_b128 v[182:185], v144 offset:3072
	v_lshl_add_u64 v[144:145], s[4:5], 0, v[136:137]
	s_add_i32 m0, s55, 0xc000
	ds_read_b128 v[186:189], v151
	ds_read_b128 v[190:193], v151 offset:1024
	ds_read_b128 v[194:197], v151 offset:2048
	ds_read_b128 v[198:201], v151 offset:3072
	ds_read_b128 v[202:205], v151 offset:4096
	ds_read_b128 v[206:209], v151 offset:5120
	ds_read_b128 v[216:219], v151 offset:6144
	ds_read_b128 v[220:223], v151 offset:7168
	global_load_lds_dwordx4 v[144:145], off
	v_lshl_add_u64 v[144:145], s[4:5], 0, v[138:139]
	s_add_i32 m0, s55, 0xe000
	s_nop 0
	global_load_lds_dwordx4 v[144:145], off
	s_waitcnt vmcnt(8)
	s_waitcnt lgkmcnt(0)
	s_barrier
	s_setprio 1
	s_waitcnt lgkmcnt(0)
	v_mfma_f32_16x16x32_bf16 v[126:129], v[140:143], v[186:189], 0
	v_mfma_f32_16x16x32_bf16 v[118:121], v[156:159], v[186:189], 0
	v_mfma_f32_16x16x32_bf16 v[110:113], v[140:143], v[194:197], 0
	v_mfma_f32_16x16x32_bf16 v[102:105], v[156:159], v[194:197], 0
	v_mfma_f32_16x16x32_bf16 v[94:97], v[140:143], v[202:205], 0
	v_mfma_f32_16x16x32_bf16 v[86:89], v[156:159], v[202:205], 0
	v_mfma_f32_16x16x32_bf16 v[76:79], v[140:143], v[216:219], 0
	v_mfma_f32_16x16x32_bf16 v[68:71], v[156:159], v[216:219], 0
	v_mfma_f32_16x16x32_bf16 v[126:129], v[152:155], v[190:193], v[126:129]
	v_mfma_f32_16x16x32_bf16 v[118:121], v[166:169], v[190:193], v[118:121]
	v_mfma_f32_16x16x32_bf16 v[110:113], v[152:155], v[198:201], v[110:113]
	v_mfma_f32_16x16x32_bf16 v[102:105], v[166:169], v[198:201], v[102:105]
	v_mfma_f32_16x16x32_bf16 v[94:97], v[152:155], v[206:209], v[94:97]
	v_mfma_f32_16x16x32_bf16 v[86:89], v[166:169], v[206:209], v[86:89]
	v_mfma_f32_16x16x32_bf16 v[76:79], v[152:155], v[220:223], v[76:79]
	v_mfma_f32_16x16x32_bf16 v[68:71], v[166:169], v[220:223], v[68:71]
	s_setprio 0
	s_setprio 1
	v_mfma_f32_16x16x32_bf16 v[122:125], v[170:173], v[186:189], 0
	v_mfma_f32_16x16x32_bf16 v[114:117], v[178:181], v[186:189], 0
	v_mfma_f32_16x16x32_bf16 v[106:109], v[170:173], v[194:197], 0
	v_mfma_f32_16x16x32_bf16 v[98:101], v[178:181], v[194:197], 0
	v_mfma_f32_16x16x32_bf16 v[90:93], v[170:173], v[202:205], 0
	v_mfma_f32_16x16x32_bf16 v[82:85], v[178:181], v[202:205], 0
	v_mfma_f32_16x16x32_bf16 v[72:75], v[170:173], v[216:219], 0
	v_mfma_f32_16x16x32_bf16 v[64:67], v[178:181], v[216:219], 0
	v_mfma_f32_16x16x32_bf16 v[122:125], v[174:177], v[190:193], v[122:125]
	v_mfma_f32_16x16x32_bf16 v[114:117], v[182:185], v[190:193], v[114:117]
	v_mfma_f32_16x16x32_bf16 v[106:109], v[174:177], v[198:201], v[106:109]
	v_mfma_f32_16x16x32_bf16 v[98:101], v[182:185], v[198:201], v[98:101]
	v_mfma_f32_16x16x32_bf16 v[90:93], v[174:177], v[206:209], v[90:93]
	v_mfma_f32_16x16x32_bf16 v[82:85], v[182:185], v[206:209], v[82:85]
	v_mfma_f32_16x16x32_bf16 v[72:75], v[174:177], v[220:223], v[72:75]
	v_mfma_f32_16x16x32_bf16 v[64:67], v[182:185], v[220:223], v[64:67]
	s_setprio 0
	s_barrier
	s_add_i32 s54, s54, s49
	v_lshl_add_u64 v[144:145], vcc, 0, v[80:81]
	s_mov_b32 m0, s54
	ds_read_b128 v[186:189], v151 offset:16384
	ds_read_b128 v[190:193], v151 offset:17408
	ds_read_b128 v[194:197], v151 offset:18432
	ds_read_b128 v[198:201], v151 offset:19456
	ds_read_b128 v[202:205], v151 offset:20480
	ds_read_b128 v[206:209], v151 offset:21504
	ds_read_b128 v[216:219], v151 offset:22528
	ds_read_b128 v[220:223], v151 offset:23552
	global_load_lds_dwordx4 v[144:145], off
	s_add_i32 m0, s54, 0x2000
	v_lshl_add_u64 v[160:161], vcc, 0, v[134:135]
	s_add_u32 vcc_lo, vcc_lo, s36
	s_addc_u32 vcc_hi, vcc_hi, 0
	s_add_i32 s53, s53, s49
	global_load_lds_dwordx4 v[160:161], off
	v_lshl_add_u64 v[224:225], vcc, 0, v[80:81]
	s_mov_b32 m0, s53
	v_lshl_add_u64 v[226:227], vcc, 0, v[134:135]
	global_load_lds_dwordx4 v[224:225], off
	s_add_i32 m0, s53, 0x2000
	v_lshl_add_u64 v[228:229], s[44:45], 0, v[130:131]
	global_load_lds_dwordx4 v[226:227], off
	s_mov_b32 m0, s55
	v_lshl_add_u64 v[230:231], s[44:45], 0, v[132:133]
	global_load_lds_dwordx4 v[228:229], off
	s_mov_b32 m0, s74
	s_nop 0
	global_load_lds_dwordx4 v[230:231], off
	s_waitcnt vmcnt(8)
	s_waitcnt lgkmcnt(0)
	s_barrier
	s_setprio 1
	s_waitcnt lgkmcnt(0)
	v_mfma_f32_16x16x32_bf16 v[60:63], v[140:143], v[186:189], 0
	v_mfma_f32_16x16x32_bf16 v[52:55], v[156:159], v[186:189], 0
	v_mfma_f32_16x16x32_bf16 v[44:47], v[140:143], v[194:197], 0
	v_mfma_f32_16x16x32_bf16 v[36:39], v[156:159], v[194:197], 0
	v_mfma_f32_16x16x32_bf16 v[28:31], v[140:143], v[202:205], 0
	v_mfma_f32_16x16x32_bf16 v[20:23], v[156:159], v[202:205], 0
	v_mfma_f32_16x16x32_bf16 v[12:15], v[140:143], v[216:219], 0
	v_mfma_f32_16x16x32_bf16 v[4:7], v[156:159], v[216:219], 0
	v_mfma_f32_16x16x32_bf16 v[60:63], v[152:155], v[190:193], v[60:63]
	v_mfma_f32_16x16x32_bf16 v[52:55], v[166:169], v[190:193], v[52:55]
	v_mfma_f32_16x16x32_bf16 v[44:47], v[152:155], v[198:201], v[44:47]
	v_mfma_f32_16x16x32_bf16 v[36:39], v[166:169], v[198:201], v[36:39]
	v_mfma_f32_16x16x32_bf16 v[28:31], v[152:155], v[206:209], v[28:31]
	v_mfma_f32_16x16x32_bf16 v[20:23], v[166:169], v[206:209], v[20:23]
	v_mfma_f32_16x16x32_bf16 v[12:15], v[152:155], v[220:223], v[12:15]
	v_mfma_f32_16x16x32_bf16 v[4:7], v[166:169], v[220:223], v[4:7]
	s_setprio 0
	s_setprio 1
	v_mfma_f32_16x16x32_bf16 v[56:59], v[170:173], v[186:189], 0
	v_mfma_f32_16x16x32_bf16 v[48:51], v[178:181], v[186:189], 0
	v_mfma_f32_16x16x32_bf16 v[40:43], v[170:173], v[194:197], 0
	v_mfma_f32_16x16x32_bf16 v[32:35], v[178:181], v[194:197], 0
	v_mfma_f32_16x16x32_bf16 v[24:27], v[170:173], v[202:205], 0
	v_mfma_f32_16x16x32_bf16 v[16:19], v[178:181], v[202:205], 0
	v_mfma_f32_16x16x32_bf16 v[8:11], v[170:173], v[216:219], 0
	v_mfma_f32_16x16x32_bf16 v[0:3], v[178:181], v[216:219], 0
	v_mfma_f32_16x16x32_bf16 v[56:59], v[174:177], v[190:193], v[56:59]
	v_mfma_f32_16x16x32_bf16 v[48:51], v[182:185], v[190:193], v[48:51]
	v_mfma_f32_16x16x32_bf16 v[40:43], v[174:177], v[198:201], v[40:43]
	v_mfma_f32_16x16x32_bf16 v[32:35], v[182:185], v[198:201], v[32:35]
	v_mfma_f32_16x16x32_bf16 v[24:27], v[174:177], v[206:209], v[24:27]
	v_mfma_f32_16x16x32_bf16 v[16:19], v[182:185], v[206:209], v[16:19]
	v_mfma_f32_16x16x32_bf16 v[8:11], v[174:177], v[220:223], v[8:11]
	v_mfma_f32_16x16x32_bf16 v[0:3], v[182:185], v[220:223], v[0:3]
	s_setprio 0
	s_barrier
	s_add_i32 s53, 0, 0x18000
	v_add_u32_e32 v146, s53, v149
	s_add_i32 s54, 0, 0x1c000
	ds_read_b128 v[140:143], v146
	ds_read_b128 v[152:155], v146 offset:1024
	ds_read_b128 v[156:159], v146 offset:2048
	ds_read_b128 v[166:169], v146 offset:3072
	v_add_u32_e32 v146, s54, v149
	ds_read_b128 v[170:173], v146
	ds_read_b128 v[174:177], v146 offset:1024
	ds_read_b128 v[178:181], v146 offset:2048
	ds_read_b128 v[182:185], v146 offset:3072
	s_add_u32 s44, s44, s36
	s_addc_u32 s45, s45, 0
	s_mov_b32 m0, s75
	v_lshl_add_u64 v[232:233], s[44:45], 0, v[130:131]
	ds_read_b128 v[186:189], v151 offset:32768
	ds_read_b128 v[190:193], v151 offset:33792
	ds_read_b128 v[194:197], v151 offset:34816
	ds_read_b128 v[198:201], v151 offset:35840
	ds_read_b128 v[202:205], v151 offset:36864
	ds_read_b128 v[206:209], v151 offset:37888
	ds_read_b128 v[216:219], v151 offset:38912
	ds_read_b128 v[220:223], v151 offset:39936
	global_load_lds_dwordx4 v[232:233], off
	v_lshl_add_u64 v[232:233], s[44:45], 0, v[132:133]
	s_mov_b32 m0, s86
	s_nop 0
	global_load_lds_dwordx4 v[232:233], off
	s_waitcnt vmcnt(8)
	s_waitcnt lgkmcnt(0)
	s_barrier
	s_setprio 1
	s_waitcnt lgkmcnt(0)
	v_mfma_f32_16x16x32_bf16 v[126:129], v[140:143], v[186:189], v[126:129]
	v_mfma_f32_16x16x32_bf16 v[118:121], v[156:159], v[186:189], v[118:121]
	v_mfma_f32_16x16x32_bf16 v[110:113], v[140:143], v[194:197], v[110:113]
	v_mfma_f32_16x16x32_bf16 v[102:105], v[156:159], v[194:197], v[102:105]
	v_mfma_f32_16x16x32_bf16 v[94:97], v[140:143], v[202:205], v[94:97]
	v_mfma_f32_16x16x32_bf16 v[86:89], v[156:159], v[202:205], v[86:89]
	v_mfma_f32_16x16x32_bf16 v[76:79], v[140:143], v[216:219], v[76:79]
	v_mfma_f32_16x16x32_bf16 v[68:71], v[156:159], v[216:219], v[68:71]
	v_mfma_f32_16x16x32_bf16 v[126:129], v[152:155], v[190:193], v[126:129]
	v_mfma_f32_16x16x32_bf16 v[118:121], v[166:169], v[190:193], v[118:121]
	v_mfma_f32_16x16x32_bf16 v[110:113], v[152:155], v[198:201], v[110:113]
	v_mfma_f32_16x16x32_bf16 v[102:105], v[166:169], v[198:201], v[102:105]
	v_mfma_f32_16x16x32_bf16 v[94:97], v[152:155], v[206:209], v[94:97]
	v_mfma_f32_16x16x32_bf16 v[86:89], v[166:169], v[206:209], v[86:89]
	v_mfma_f32_16x16x32_bf16 v[76:79], v[152:155], v[220:223], v[76:79]
	v_mfma_f32_16x16x32_bf16 v[68:71], v[166:169], v[220:223], v[68:71]
	s_setprio 0
	s_setprio 1
	v_mfma_f32_16x16x32_bf16 v[122:125], v[170:173], v[186:189], v[122:125]
	v_mfma_f32_16x16x32_bf16 v[114:117], v[178:181], v[186:189], v[114:117]
	v_mfma_f32_16x16x32_bf16 v[106:109], v[170:173], v[194:197], v[106:109]
	v_mfma_f32_16x16x32_bf16 v[98:101], v[178:181], v[194:197], v[98:101]
	v_mfma_f32_16x16x32_bf16 v[90:93], v[170:173], v[202:205], v[90:93]
	v_mfma_f32_16x16x32_bf16 v[82:85], v[178:181], v[202:205], v[82:85]
	v_mfma_f32_16x16x32_bf16 v[72:75], v[170:173], v[216:219], v[72:75]
	v_mfma_f32_16x16x32_bf16 v[64:67], v[178:181], v[216:219], v[64:67]
	v_mfma_f32_16x16x32_bf16 v[122:125], v[174:177], v[190:193], v[122:125]
	v_mfma_f32_16x16x32_bf16 v[114:117], v[182:185], v[190:193], v[114:117]
	v_mfma_f32_16x16x32_bf16 v[106:109], v[174:177], v[198:201], v[106:109]
	v_mfma_f32_16x16x32_bf16 v[98:101], v[182:185], v[198:201], v[98:101]
	v_mfma_f32_16x16x32_bf16 v[90:93], v[174:177], v[206:209], v[90:93]
	v_mfma_f32_16x16x32_bf16 v[82:85], v[182:185], v[206:209], v[82:85]
	v_mfma_f32_16x16x32_bf16 v[72:75], v[174:177], v[220:223], v[72:75]
	v_mfma_f32_16x16x32_bf16 v[64:67], v[182:185], v[220:223], v[64:67]
	s_setprio 0
	s_barrier
	s_add_i32 s44, s53, s49
	v_lshl_add_u64 v[144:145], v[144:145], 0, s[0:1]
	s_mov_b32 m0, s44
	ds_read_b128 v[186:189], v151 offset:49152
	ds_read_b128 v[190:193], v151 offset:50176
	ds_read_b128 v[194:197], v151 offset:51200
	ds_read_b128 v[198:201], v151 offset:52224
	ds_read_b128 v[202:205], v151 offset:53248
	ds_read_b128 v[206:209], v151 offset:54272
	ds_read_b128 v[216:219], v151 offset:55296
	ds_read_b128 v[220:223], v151 offset:56320
	global_load_lds_dwordx4 v[144:145], off
	v_lshl_add_u64 v[144:145], v[160:161], 0, s[0:1]
	s_add_i32 m0, s44, 0x2000
	s_add_i32 s44, s54, s49
	global_load_lds_dwordx4 v[144:145], off
	v_lshl_add_u64 v[144:145], v[224:225], 0, s[0:1]
	s_mov_b32 m0, s44
	s_nop 0
	global_load_lds_dwordx4 v[144:145], off
	v_lshl_add_u64 v[144:145], v[226:227], 0, s[0:1]
	s_add_i32 m0, s44, 0x2000
	s_nop 0
	global_load_lds_dwordx4 v[144:145], off
	v_lshl_add_u64 v[144:145], v[228:229], 0, s[0:1]
	s_mov_b32 m0, s88
	s_nop 0
	global_load_lds_dwordx4 v[144:145], off
	v_lshl_add_u64 v[144:145], v[230:231], 0, s[0:1]
	s_mov_b32 m0, s89
	s_nop 0
	global_load_lds_dwordx4 v[144:145], off
	s_waitcnt vmcnt(8)
	s_waitcnt lgkmcnt(0)
	s_barrier
	s_setprio 1
	s_waitcnt lgkmcnt(0)
	v_mfma_f32_16x16x32_bf16 v[60:63], v[140:143], v[186:189], v[60:63]
	v_mfma_f32_16x16x32_bf16 v[52:55], v[156:159], v[186:189], v[52:55]
	v_mfma_f32_16x16x32_bf16 v[44:47], v[140:143], v[194:197], v[44:47]
	v_mfma_f32_16x16x32_bf16 v[36:39], v[156:159], v[194:197], v[36:39]
	v_mfma_f32_16x16x32_bf16 v[28:31], v[140:143], v[202:205], v[28:31]
	v_mfma_f32_16x16x32_bf16 v[20:23], v[156:159], v[202:205], v[20:23]
	v_mfma_f32_16x16x32_bf16 v[12:15], v[140:143], v[216:219], v[12:15]
	v_mfma_f32_16x16x32_bf16 v[4:7], v[156:159], v[216:219], v[4:7]
	v_mfma_f32_16x16x32_bf16 v[60:63], v[152:155], v[190:193], v[60:63]
	v_mfma_f32_16x16x32_bf16 v[52:55], v[166:169], v[190:193], v[52:55]
	v_mfma_f32_16x16x32_bf16 v[44:47], v[152:155], v[198:201], v[44:47]
	v_mfma_f32_16x16x32_bf16 v[36:39], v[166:169], v[198:201], v[36:39]
	v_mfma_f32_16x16x32_bf16 v[28:31], v[152:155], v[206:209], v[28:31]
	v_mfma_f32_16x16x32_bf16 v[20:23], v[166:169], v[206:209], v[20:23]
	v_mfma_f32_16x16x32_bf16 v[12:15], v[152:155], v[220:223], v[12:15]
	v_mfma_f32_16x16x32_bf16 v[4:7], v[166:169], v[220:223], v[4:7]
	s_setprio 0
	s_setprio 1
	v_mfma_f32_16x16x32_bf16 v[56:59], v[170:173], v[186:189], v[56:59]
	v_mfma_f32_16x16x32_bf16 v[48:51], v[178:181], v[186:189], v[48:51]
	v_mfma_f32_16x16x32_bf16 v[40:43], v[170:173], v[194:197], v[40:43]
	v_mfma_f32_16x16x32_bf16 v[32:35], v[178:181], v[194:197], v[32:35]
	v_mfma_f32_16x16x32_bf16 v[24:27], v[170:173], v[202:205], v[24:27]
	v_mfma_f32_16x16x32_bf16 v[16:19], v[178:181], v[202:205], v[16:19]
	v_mfma_f32_16x16x32_bf16 v[8:11], v[170:173], v[216:219], v[8:11]
	v_mfma_f32_16x16x32_bf16 v[0:3], v[178:181], v[216:219], v[0:3]
	v_mfma_f32_16x16x32_bf16 v[56:59], v[174:177], v[190:193], v[56:59]
	v_mfma_f32_16x16x32_bf16 v[48:51], v[182:185], v[190:193], v[48:51]
	v_mfma_f32_16x16x32_bf16 v[40:43], v[174:177], v[198:201], v[40:43]
	v_mfma_f32_16x16x32_bf16 v[32:35], v[182:185], v[198:201], v[32:35]
	v_mfma_f32_16x16x32_bf16 v[24:27], v[174:177], v[206:209], v[24:27]
	v_mfma_f32_16x16x32_bf16 v[16:19], v[182:185], v[206:209], v[16:19]
	v_mfma_f32_16x16x32_bf16 v[8:11], v[174:177], v[220:223], v[8:11]
	v_mfma_f32_16x16x32_bf16 v[0:3], v[182:185], v[220:223], v[0:3]
	s_setprio 0
	s_barrier
	s_add_u32 s4, s4, 0x100
	s_addc_u32 s5, s5, 0
	s_add_u32 s46, s46, 0x100
	s_addc_u32 s47, s47, 0
	s_cmp_ge_u32 s76, s87
	s_mov_b32 s44, s76
	s_cbranch_scc1 .Lpeel_done_603

.LBB0_622:
	s_nop 0
	v_pk_mul_f32 v[12:13], v[12:13], v[44:45] op_sel_hi:[1,0]
	v_pk_mul_f32 v[8:9], v[8:9], v[44:45] op_sel_hi:[1,0]
	v_mul_f32_e32 v18, 0xbfb8aa3b, v12
	v_pk_mul_f32 v[8:9], v[12:13], v[8:9]
	v_mul_f32_e32 v12, 0xbfb8aa3b, v13
	v_exp_f32_e32 v12, v12
	v_pk_mul_f32 v[10:11], v[10:11], v[44:45] op_sel_hi:[1,0]
	v_pk_mul_f32 v[4:5], v[4:5], v[44:45] op_sel_hi:[1,0]
	v_pk_mul_f32 v[0:1], v[0:1], v[44:45] op_sel_hi:[1,0]
	v_add_f32_e32 v12, 1.0, v12
	v_rcp_f32_e32 v19, v12
	v_pk_mul_f32 v[12:13], v[14:15], v[44:45] op_sel_hi:[1,0]
	v_pk_mul_f32 v[0:1], v[4:5], v[0:1]
	v_mul_f32_e32 v14, 0xbfb8aa3b, v12
	v_pk_mul_f32 v[10:11], v[12:13], v[10:11]
	v_mul_f32_e32 v12, 0xbfb8aa3b, v13
	v_exp_f32_e32 v12, v12
	v_pk_mul_f32 v[2:3], v[2:3], v[44:45] op_sel_hi:[1,0]
	v_exp_f32_e32 v18, v18
	v_exp_f32_e32 v14, v14
	v_add_f32_e32 v12, 1.0, v12
	v_rcp_f32_e32 v15, v12
	v_mul_f32_e32 v12, 0xbfb8aa3b, v4
	v_mul_f32_e32 v4, 0xbfb8aa3b, v5
	v_exp_f32_e32 v12, v12
	v_exp_f32_e32 v4, v4
	v_add_f32_e32 v18, 1.0, v18
	v_add_f32_e32 v14, 1.0, v14
	v_add_f32_e32 v12, 1.0, v12
	v_add_f32_e32 v4, 1.0, v4
	v_rcp_f32_e32 v12, v12
	v_rcp_f32_e32 v13, v4
	v_rcp_f32_e32 v18, v18
	v_rcp_f32_e32 v14, v14
	v_add_u32_e32 v16, 0xb0, v140
	v_pk_mul_f32 v[4:5], v[0:1], v[12:13]
	v_pk_mul_f32 v[0:1], v[6:7], v[44:45] op_sel_hi:[1,0]
	v_mad_i64_i32 v[16:17], s[4:5], s82, v16, 0
	v_mul_f32_e32 v6, 0xbfb8aa3b, v0
	v_pk_mul_f32 v[2:3], v[0:1], v[2:3]
	v_mul_f32_e32 v0, 0xbfb8aa3b, v1
	v_exp_f32_e32 v6, v6
	v_exp_f32_e32 v0, v0
	v_lshl_add_u64 v[16:17], v[16:17], 1, s[62:63]
	v_pk_mul_f32 v[8:9], v[8:9], v[18:19]
	v_add_f32_e32 v6, 1.0, v6
	v_add_f32_e32 v0, 1.0, v0
	v_rcp_f32_e32 v6, v6
	v_rcp_f32_e32 v7, v0
	v_pk_mul_f32 v[10:11], v[10:11], v[14:15]
	v_lshl_add_u64 v[16:17], v[144:145], 1, v[16:17]
	v_cvt_pk_bf16_f32 v0, v8, v9
	v_pk_mul_f32 v[6:7], v[2:3], v[6:7]
	v_cvt_pk_bf16_f32 v1, v10, v11
	v_cvt_pk_bf16_f32 v2, v4, v5
	v_cvt_pk_bf16_f32 v3, v6, v7
	s_mov_b64 s[4:5], -1
	s_and_b64 vcc, exec, s[2:3]
	global_store_dwordx4 v[16:17], v[0:3], off
	s_cbranch_vccnz .LBB0_591
	s_andn2_b64 vcc, exec, s[8:9]
	s_cbranch_vccnz .LBB0_590
	s_branch .LBB0_590

.LBB0_650:
	s_add_u32 s4, s46, 0x80
	s_addc_u32 s5, s47, 0
	s_add_u32 s46, s44, 0x100
	s_addc_u32 s47, s45, 0
	s_mov_b32 s44, 0
	s_andn2_b64 vcc, exec, s[8:9]
	s_cbranch_vccnz .Lnb_651
	s_cmp_eq_u32 s93, 1
	s_cbranch_scc1 .Lnb_651
	s_barrier
.Lnb_651:
	s_add_i32 s77, s44, 2
	s_add_u32 vcc_lo, s4, 0x80
	s_addc_u32 s45, s5, 0
	s_add_i32 s53, 0, 0x10000
	s_cmp_eq_u32 s80, s44
	s_cselect_b32 s45, s41, s45
	s_cselect_b32 s44, s40, vcc_lo
	v_add_u32_e32 v144, s53, v149
	s_cselect_b32 vcc_hi, s85, s47
	s_cselect_b32 vcc_lo, s84, s46
	s_add_i32 s54, 0, 0x14000
	ds_read_b128 v[140:143], v144
	ds_read_b128 v[152:155], v144 offset:1024
	ds_read_b128 v[156:159], v144 offset:2048
	ds_read_b128 v[166:169], v144 offset:3072
	v_add_u32_e32 v144, s54, v149
	ds_read_b128 v[170:173], v144
	ds_read_b128 v[174:177], v144 offset:1024
	ds_read_b128 v[178:181], v144 offset:2048
	ds_read_b128 v[182:185], v144 offset:3072
	v_lshl_add_u64 v[144:145], s[4:5], 0, v[136:137]
	s_add_i32 m0, s49, 0xc000
	ds_read_b128 v[186:189], v151
	ds_read_b128 v[190:193], v151 offset:1024
	ds_read_b128 v[194:197], v151 offset:2048
	ds_read_b128 v[198:201], v151 offset:3072
	ds_read_b128 v[202:205], v151 offset:4096
	ds_read_b128 v[206:209], v151 offset:5120
	ds_read_b128 v[216:219], v151 offset:6144
	ds_read_b128 v[220:223], v151 offset:7168
	global_load_lds_dwordx4 v[144:145], off
	v_lshl_add_u64 v[144:145], s[4:5], 0, v[138:139]
	s_add_i32 m0, s49, 0xe000
	s_nop 0
	global_load_lds_dwordx4 v[144:145], off
	s_waitcnt vmcnt(8)
	s_waitcnt lgkmcnt(0)
	s_barrier
	s_setprio 1
	s_waitcnt lgkmcnt(0)
	v_mfma_f32_16x16x32_bf16 v[126:129], v[140:143], v[186:189], 0
	v_mfma_f32_16x16x32_bf16 v[122:125], v[156:159], v[186:189], 0
	v_mfma_f32_16x16x32_bf16 v[110:113], v[140:143], v[194:197], 0
	v_mfma_f32_16x16x32_bf16 v[106:109], v[156:159], v[194:197], 0
	v_mfma_f32_16x16x32_bf16 v[94:97], v[140:143], v[202:205], 0
	v_mfma_f32_16x16x32_bf16 v[90:93], v[156:159], v[202:205], 0
	v_mfma_f32_16x16x32_bf16 v[76:79], v[140:143], v[216:219], 0
	v_mfma_f32_16x16x32_bf16 v[72:75], v[156:159], v[216:219], 0
	v_mfma_f32_16x16x32_bf16 v[126:129], v[152:155], v[190:193], v[126:129]
	v_mfma_f32_16x16x32_bf16 v[122:125], v[166:169], v[190:193], v[122:125]
	v_mfma_f32_16x16x32_bf16 v[110:113], v[152:155], v[198:201], v[110:113]
	v_mfma_f32_16x16x32_bf16 v[106:109], v[166:169], v[198:201], v[106:109]
	v_mfma_f32_16x16x32_bf16 v[94:97], v[152:155], v[206:209], v[94:97]
	v_mfma_f32_16x16x32_bf16 v[90:93], v[166:169], v[206:209], v[90:93]
	v_mfma_f32_16x16x32_bf16 v[76:79], v[152:155], v[220:223], v[76:79]
	v_mfma_f32_16x16x32_bf16 v[72:75], v[166:169], v[220:223], v[72:75]
	s_setprio 0
	s_setprio 1
	v_mfma_f32_16x16x32_bf16 v[118:121], v[170:173], v[186:189], 0
	v_mfma_f32_16x16x32_bf16 v[114:117], v[178:181], v[186:189], 0
	v_mfma_f32_16x16x32_bf16 v[102:105], v[170:173], v[194:197], 0
	v_mfma_f32_16x16x32_bf16 v[98:101], v[178:181], v[194:197], 0
	v_mfma_f32_16x16x32_bf16 v[86:89], v[170:173], v[202:205], 0
	v_mfma_f32_16x16x32_bf16 v[82:85], v[178:181], v[202:205], 0
	v_mfma_f32_16x16x32_bf16 v[68:71], v[170:173], v[216:219], 0
	v_mfma_f32_16x16x32_bf16 v[64:67], v[178:181], v[216:219], 0
	v_mfma_f32_16x16x32_bf16 v[118:121], v[174:177], v[190:193], v[118:121]
	v_mfma_f32_16x16x32_bf16 v[114:117], v[182:185], v[190:193], v[114:117]
	v_mfma_f32_16x16x32_bf16 v[102:105], v[174:177], v[198:201], v[102:105]
	v_mfma_f32_16x16x32_bf16 v[98:101], v[182:185], v[198:201], v[98:101]
	v_mfma_f32_16x16x32_bf16 v[86:89], v[174:177], v[206:209], v[86:89]
	v_mfma_f32_16x16x32_bf16 v[82:85], v[182:185], v[206:209], v[82:85]
	v_mfma_f32_16x16x32_bf16 v[68:71], v[174:177], v[220:223], v[68:71]
	v_mfma_f32_16x16x32_bf16 v[64:67], v[182:185], v[220:223], v[64:67]
	s_setprio 0
	s_barrier
	s_add_i32 s53, s53, s48
	v_lshl_add_u64 v[144:145], vcc, 0, v[80:81]
	s_mov_b32 m0, s53
	ds_read_b128 v[186:189], v151 offset:16384
	ds_read_b128 v[190:193], v151 offset:17408
	ds_read_b128 v[194:197], v151 offset:18432
	ds_read_b128 v[198:201], v151 offset:19456
	ds_read_b128 v[202:205], v151 offset:20480
	ds_read_b128 v[206:209], v151 offset:21504
	ds_read_b128 v[216:219], v151 offset:22528
	ds_read_b128 v[220:223], v151 offset:23552
	global_load_lds_dwordx4 v[144:145], off
	s_add_i32 m0, s53, 0x2000
	v_lshl_add_u64 v[160:161], vcc, 0, v[134:135]
	s_add_u32 vcc_lo, vcc_lo, s36
	s_addc_u32 vcc_hi, vcc_hi, 0
	s_add_i32 s53, s54, s48
	global_load_lds_dwordx4 v[160:161], off
	v_lshl_add_u64 v[224:225], vcc, 0, v[80:81]
	s_mov_b32 m0, s53
	v_lshl_add_u64 v[226:227], vcc, 0, v[134:135]
	global_load_lds_dwordx4 v[224:225], off
	s_add_i32 m0, s53, 0x2000
	v_lshl_add_u64 v[228:229], s[44:45], 0, v[130:131]
	global_load_lds_dwordx4 v[226:227], off
	s_mov_b32 m0, s49
	v_lshl_add_u64 v[230:231], s[44:45], 0, v[132:133]
	global_load_lds_dwordx4 v[228:229], off
	s_mov_b32 m0, s50
	s_nop 0
	global_load_lds_dwordx4 v[230:231], off
	s_waitcnt vmcnt(8)
	s_waitcnt lgkmcnt(0)
	s_barrier
	s_setprio 1
	s_waitcnt lgkmcnt(0)
	v_mfma_f32_16x16x32_bf16 v[60:63], v[140:143], v[186:189], 0
	v_mfma_f32_16x16x32_bf16 v[56:59], v[156:159], v[186:189], 0
	v_mfma_f32_16x16x32_bf16 v[44:47], v[140:143], v[194:197], 0
	v_mfma_f32_16x16x32_bf16 v[40:43], v[156:159], v[194:197], 0
	v_mfma_f32_16x16x32_bf16 v[28:31], v[140:143], v[202:205], 0
	v_mfma_f32_16x16x32_bf16 v[24:27], v[156:159], v[202:205], 0
	v_mfma_f32_16x16x32_bf16 v[12:15], v[140:143], v[216:219], 0
	v_mfma_f32_16x16x32_bf16 v[8:11], v[156:159], v[216:219], 0
	v_mfma_f32_16x16x32_bf16 v[60:63], v[152:155], v[190:193], v[60:63]
	v_mfma_f32_16x16x32_bf16 v[56:59], v[166:169], v[190:193], v[56:59]
	v_mfma_f32_16x16x32_bf16 v[44:47], v[152:155], v[198:201], v[44:47]
	v_mfma_f32_16x16x32_bf16 v[40:43], v[166:169], v[198:201], v[40:43]
	v_mfma_f32_16x16x32_bf16 v[28:31], v[152:155], v[206:209], v[28:31]
	v_mfma_f32_16x16x32_bf16 v[24:27], v[166:169], v[206:209], v[24:27]
	v_mfma_f32_16x16x32_bf16 v[12:15], v[152:155], v[220:223], v[12:15]
	v_mfma_f32_16x16x32_bf16 v[8:11], v[166:169], v[220:223], v[8:11]
	s_setprio 0
	s_setprio 1
	v_mfma_f32_16x16x32_bf16 v[52:55], v[170:173], v[186:189], 0
	v_mfma_f32_16x16x32_bf16 v[48:51], v[178:181], v[186:189], 0
	v_mfma_f32_16x16x32_bf16 v[36:39], v[170:173], v[194:197], 0
	v_mfma_f32_16x16x32_bf16 v[32:35], v[178:181], v[194:197], 0
	v_mfma_f32_16x16x32_bf16 v[20:23], v[170:173], v[202:205], 0
	v_mfma_f32_16x16x32_bf16 v[16:19], v[178:181], v[202:205], 0
	v_mfma_f32_16x16x32_bf16 v[4:7], v[170:173], v[216:219], 0
	v_mfma_f32_16x16x32_bf16 v[0:3], v[178:181], v[216:219], 0
	v_mfma_f32_16x16x32_bf16 v[52:55], v[174:177], v[190:193], v[52:55]
	v_mfma_f32_16x16x32_bf16 v[48:51], v[182:185], v[190:193], v[48:51]
	v_mfma_f32_16x16x32_bf16 v[36:39], v[174:177], v[198:201], v[36:39]
	v_mfma_f32_16x16x32_bf16 v[32:35], v[182:185], v[198:201], v[32:35]
	v_mfma_f32_16x16x32_bf16 v[20:23], v[174:177], v[206:209], v[20:23]
	v_mfma_f32_16x16x32_bf16 v[16:19], v[182:185], v[206:209], v[16:19]
	v_mfma_f32_16x16x32_bf16 v[4:7], v[174:177], v[220:223], v[4:7]
	v_mfma_f32_16x16x32_bf16 v[0:3], v[182:185], v[220:223], v[0:3]
	s_setprio 0
	s_barrier
	s_add_i32 s53, 0, 0x18000
	v_add_u32_e32 v146, s53, v149
	s_add_i32 s54, 0, 0x1c000
	ds_read_b128 v[140:143], v146
	ds_read_b128 v[152:155], v146 offset:1024
	ds_read_b128 v[156:159], v146 offset:2048
	ds_read_b128 v[166:169], v146 offset:3072
	v_add_u32_e32 v146, s54, v149
	ds_read_b128 v[170:173], v146
	ds_read_b128 v[174:177], v146 offset:1024
	ds_read_b128 v[178:181], v146 offset:2048
	ds_read_b128 v[182:185], v146 offset:3072
	s_add_u32 s44, s44, s36
	s_addc_u32 s45, s45, 0
	s_mov_b32 m0, s55
	v_lshl_add_u64 v[232:233], s[44:45], 0, v[130:131]
	ds_read_b128 v[186:189], v151 offset:32768
	ds_read_b128 v[190:193], v151 offset:33792
	ds_read_b128 v[194:197], v151 offset:34816
	ds_read_b128 v[198:201], v151 offset:35840
	ds_read_b128 v[202:205], v151 offset:36864
	ds_read_b128 v[206:209], v151 offset:37888
	ds_read_b128 v[216:219], v151 offset:38912
	ds_read_b128 v[220:223], v151 offset:39936
	global_load_lds_dwordx4 v[232:233], off
	v_lshl_add_u64 v[232:233], s[44:45], 0, v[132:133]
	s_mov_b32 m0, s56
	s_nop 0
	global_load_lds_dwordx4 v[232:233], off
	s_waitcnt vmcnt(8)
	s_waitcnt lgkmcnt(0)
	s_barrier
	s_setprio 1
	s_waitcnt lgkmcnt(0)
	v_mfma_f32_16x16x32_bf16 v[126:129], v[140:143], v[186:189], v[126:129]
	v_mfma_f32_16x16x32_bf16 v[122:125], v[156:159], v[186:189], v[122:125]
	v_mfma_f32_16x16x32_bf16 v[110:113], v[140:143], v[194:197], v[110:113]
	v_mfma_f32_16x16x32_bf16 v[106:109], v[156:159], v[194:197], v[106:109]
	v_mfma_f32_16x16x32_bf16 v[94:97], v[140:143], v[202:205], v[94:97]
	v_mfma_f32_16x16x32_bf16 v[90:93], v[156:159], v[202:205], v[90:93]
	v_mfma_f32_16x16x32_bf16 v[76:79], v[140:143], v[216:219], v[76:79]
	v_mfma_f32_16x16x32_bf16 v[72:75], v[156:159], v[216:219], v[72:75]
	v_mfma_f32_16x16x32_bf16 v[126:129], v[152:155], v[190:193], v[126:129]
	v_mfma_f32_16x16x32_bf16 v[122:125], v[166:169], v[190:193], v[122:125]
	v_mfma_f32_16x16x32_bf16 v[110:113], v[152:155], v[198:201], v[110:113]
	v_mfma_f32_16x16x32_bf16 v[106:109], v[166:169], v[198:201], v[106:109]
	v_mfma_f32_16x16x32_bf16 v[94:97], v[152:155], v[206:209], v[94:97]
	v_mfma_f32_16x16x32_bf16 v[90:93], v[166:169], v[206:209], v[90:93]
	v_mfma_f32_16x16x32_bf16 v[76:79], v[152:155], v[220:223], v[76:79]
	v_mfma_f32_16x16x32_bf16 v[72:75], v[166:169], v[220:223], v[72:75]
	s_setprio 0
	s_setprio 1
	v_mfma_f32_16x16x32_bf16 v[118:121], v[170:173], v[186:189], v[118:121]
	v_mfma_f32_16x16x32_bf16 v[114:117], v[178:181], v[186:189], v[114:117]
	v_mfma_f32_16x16x32_bf16 v[102:105], v[170:173], v[194:197], v[102:105]
	v_mfma_f32_16x16x32_bf16 v[98:101], v[178:181], v[194:197], v[98:101]
	v_mfma_f32_16x16x32_bf16 v[86:89], v[170:173], v[202:205], v[86:89]
	v_mfma_f32_16x16x32_bf16 v[82:85], v[178:181], v[202:205], v[82:85]
	v_mfma_f32_16x16x32_bf16 v[68:71], v[170:173], v[216:219], v[68:71]
	v_mfma_f32_16x16x32_bf16 v[64:67], v[178:181], v[216:219], v[64:67]
	v_mfma_f32_16x16x32_bf16 v[118:121], v[174:177], v[190:193], v[118:121]
	v_mfma_f32_16x16x32_bf16 v[114:117], v[182:185], v[190:193], v[114:117]
	v_mfma_f32_16x16x32_bf16 v[102:105], v[174:177], v[198:201], v[102:105]
	v_mfma_f32_16x16x32_bf16 v[98:101], v[182:185], v[198:201], v[98:101]
	v_mfma_f32_16x16x32_bf16 v[86:89], v[174:177], v[206:209], v[86:89]
	v_mfma_f32_16x16x32_bf16 v[82:85], v[182:185], v[206:209], v[82:85]
	v_mfma_f32_16x16x32_bf16 v[68:71], v[174:177], v[220:223], v[68:71]
	v_mfma_f32_16x16x32_bf16 v[64:67], v[182:185], v[220:223], v[64:67]
	s_setprio 0
	s_barrier
	s_add_i32 s44, s53, s48
	v_lshl_add_u64 v[144:145], v[144:145], 0, s[0:1]
	s_mov_b32 m0, s44
	ds_read_b128 v[186:189], v151 offset:49152
	ds_read_b128 v[190:193], v151 offset:50176
	ds_read_b128 v[194:197], v151 offset:51200
	ds_read_b128 v[198:201], v151 offset:52224
	ds_read_b128 v[202:205], v151 offset:53248
	ds_read_b128 v[206:209], v151 offset:54272
	ds_read_b128 v[216:219], v151 offset:55296
	ds_read_b128 v[220:223], v151 offset:56320
	global_load_lds_dwordx4 v[144:145], off
	v_lshl_add_u64 v[144:145], v[160:161], 0, s[0:1]
	s_add_i32 m0, s44, 0x2000
	s_add_i32 s44, s54, s48
	global_load_lds_dwordx4 v[144:145], off
	v_lshl_add_u64 v[144:145], v[224:225], 0, s[0:1]
	s_mov_b32 m0, s44
	s_nop 0
	global_load_lds_dwordx4 v[144:145], off
	v_lshl_add_u64 v[144:145], v[226:227], 0, s[0:1]
	s_add_i32 m0, s44, 0x2000
	s_nop 0
	global_load_lds_dwordx4 v[144:145], off
	v_lshl_add_u64 v[144:145], v[228:229], 0, s[0:1]
	s_mov_b32 m0, s74
	s_nop 0
	global_load_lds_dwordx4 v[144:145], off
	v_lshl_add_u64 v[144:145], v[230:231], 0, s[0:1]
	s_mov_b32 m0, s75
	s_nop 0
	global_load_lds_dwordx4 v[144:145], off
	s_waitcnt vmcnt(8)
	s_waitcnt lgkmcnt(0)
	s_barrier
	s_setprio 1
	s_waitcnt lgkmcnt(0)
	v_mfma_f32_16x16x32_bf16 v[60:63], v[140:143], v[186:189], v[60:63]
	v_mfma_f32_16x16x32_bf16 v[56:59], v[156:159], v[186:189], v[56:59]
	v_mfma_f32_16x16x32_bf16 v[44:47], v[140:143], v[194:197], v[44:47]
	v_mfma_f32_16x16x32_bf16 v[40:43], v[156:159], v[194:197], v[40:43]
	v_mfma_f32_16x16x32_bf16 v[28:31], v[140:143], v[202:205], v[28:31]
	v_mfma_f32_16x16x32_bf16 v[24:27], v[156:159], v[202:205], v[24:27]
	v_mfma_f32_16x16x32_bf16 v[12:15], v[140:143], v[216:219], v[12:15]
	v_mfma_f32_16x16x32_bf16 v[8:11], v[156:159], v[216:219], v[8:11]
	v_mfma_f32_16x16x32_bf16 v[60:63], v[152:155], v[190:193], v[60:63]
	v_mfma_f32_16x16x32_bf16 v[56:59], v[166:169], v[190:193], v[56:59]
	v_mfma_f32_16x16x32_bf16 v[44:47], v[152:155], v[198:201], v[44:47]
	v_mfma_f32_16x16x32_bf16 v[40:43], v[166:169], v[198:201], v[40:43]
	v_mfma_f32_16x16x32_bf16 v[28:31], v[152:155], v[206:209], v[28:31]
	v_mfma_f32_16x16x32_bf16 v[24:27], v[166:169], v[206:209], v[24:27]
	v_mfma_f32_16x16x32_bf16 v[12:15], v[152:155], v[220:223], v[12:15]
	v_mfma_f32_16x16x32_bf16 v[8:11], v[166:169], v[220:223], v[8:11]
	s_setprio 0
	s_setprio 1
	v_mfma_f32_16x16x32_bf16 v[52:55], v[170:173], v[186:189], v[52:55]
	v_mfma_f32_16x16x32_bf16 v[48:51], v[178:181], v[186:189], v[48:51]
	v_mfma_f32_16x16x32_bf16 v[36:39], v[170:173], v[194:197], v[36:39]
	v_mfma_f32_16x16x32_bf16 v[32:35], v[178:181], v[194:197], v[32:35]
	v_mfma_f32_16x16x32_bf16 v[20:23], v[170:173], v[202:205], v[20:23]
	v_mfma_f32_16x16x32_bf16 v[16:19], v[178:181], v[202:205], v[16:19]
	v_mfma_f32_16x16x32_bf16 v[4:7], v[170:173], v[216:219], v[4:7]
	v_mfma_f32_16x16x32_bf16 v[0:3], v[178:181], v[216:219], v[0:3]
	v_mfma_f32_16x16x32_bf16 v[52:55], v[174:177], v[190:193], v[52:55]
	v_mfma_f32_16x16x32_bf16 v[48:51], v[182:185], v[190:193], v[48:51]
	v_mfma_f32_16x16x32_bf16 v[36:39], v[174:177], v[198:201], v[36:39]
	v_mfma_f32_16x16x32_bf16 v[32:35], v[182:185], v[198:201], v[32:35]
	v_mfma_f32_16x16x32_bf16 v[20:23], v[174:177], v[206:209], v[20:23]
	v_mfma_f32_16x16x32_bf16 v[16:19], v[182:185], v[206:209], v[16:19]
	v_mfma_f32_16x16x32_bf16 v[4:7], v[174:177], v[220:223], v[4:7]
	v_mfma_f32_16x16x32_bf16 v[0:3], v[182:185], v[220:223], v[0:3]
	s_setprio 0
	s_barrier
	s_add_u32 s4, s4, 0x100
	s_addc_u32 s5, s5, 0
	s_add_u32 s46, s46, 0x100
	s_addc_u32 s47, s47, 0
	s_cmp_ge_u32 s77, s83
	s_mov_b32 s44, s77
	s_cbranch_scc1 .Lpeel_done_651

.LBB0_670:
	s_nop 0
	v_add_u32_e32 v16, 0xb0, v140
	v_mad_i64_i32 v[16:17], s[4:5], s82, v16, 0
	v_lshl_add_u64 v[16:17], v[16:17], 1, s[62:63]
	s_nop 0
	v_pk_mul_f32 v[14:15], v[14:15], v[32:33] op_sel_hi:[1,0]
	v_pk_mul_f32 v[12:13], v[12:13], v[32:33] op_sel_hi:[1,0]
	v_pk_mul_f32 v[18:19], v[10:11], v[32:33] op_sel_hi:[1,0]
	v_pk_mul_f32 v[10:11], v[8:9], v[32:33] op_sel_hi:[1,0]
	v_lshl_add_u64 v[16:17], v[142:143], 1, v[16:17]
	v_cvt_pk_bf16_f32 v8, v12, v13
	v_cvt_pk_bf16_f32 v9, v14, v15
	v_cvt_pk_bf16_f32 v10, v10, v11
	v_cvt_pk_bf16_f32 v11, v18, v19
	global_store_dwordx4 v[16:17], v[8:11], off
	v_pk_mul_f32 v[6:7], v[6:7], v[32:33] op_sel_hi:[1,0]
	v_pk_mul_f32 v[4:5], v[4:5], v[32:33] op_sel_hi:[1,0]
	v_pk_mul_f32 v[8:9], v[2:3], v[32:33] op_sel_hi:[1,0]
	v_pk_mul_f32 v[2:3], v[0:1], v[32:33] op_sel_hi:[1,0]
	v_cvt_pk_bf16_f32 v0, v4, v5
	v_cvt_pk_bf16_f32 v1, v6, v7
	v_cvt_pk_bf16_f32 v2, v2, v3
	v_cvt_pk_bf16_f32 v3, v8, v9
	s_and_b64 vcc, exec, s[2:3]
	s_mov_b64 s[2:3], -1
	global_store_dwordx4 v[16:17], v[0:3], off offset:256
	s_cbranch_vccnz .LBB0_639
	s_andn2_b64 vcc, exec, s[8:9]
	s_cbranch_vccnz .LBB0_638
	s_branch .LBB0_638
